# v42 + channel DFT exploits the output-index symmetry of the DFT matrices: only outputs 0..31 of each 64-group go through the f32 MFMA, 33..63 are mirror copies (sin negated), 32 is an alternating sum
# speedup vs baseline: 1.0098x; 1.0031x over previous
; __device__ __forceinline__ void phase_prep(const Params& P, int l, unsigned char* lds) {
;     ...
; #pragma unroll 2
;             for (int c = 0; c < 64; ++c) {
;                 float cv[4], sv[4];
; #pragma unroll
;                 for (int q = 0; q < 4; ++q) { const float rev = (float)((c * (cp0 + q)) & 63) * (1.0f / 64.0f); cv[q] = __builtin_amdgcn_cosf(rev) * 0.125f; sv[q] = __builtin_amdgcn_sinf(rev) * 0.125f; }
; #pragma unroll
;                 for (int t = 0; t < 8; ++t) { const float u = ub[t * 256 + c], u2 = ub2[t * 256 + c];
; #pragma unroll
;                     for (int q = 0; q < 4; ++q) { aC[q][t] += u * cv[q]; aS[q][t] += u2 * ((t == 0 && sp0) ? cv[q] : sv[q]); } }
.Ldft_st_ctx:
	s_lshl_b32 s7, s12, 13
	v_lshl_add_u32 v35, v32, 2, s7
	v_add_u32_e32 v36, 0x10000, v35
	v_add_u32_e32 v41, 32, v34
	v_mul_u32_u24_e32 v120, v33, v34
	v_mul_u32_u24_e32 v121, v33, v41
	v_lshlrev_b32_e32 v122, 1, v34
	v_lshlrev_b32_e32 v123, 1, v41
	v_and_b32_e32 v41, 63, v120
	v_cvt_f32_u32_e32 v41, v41
	v_mul_f32_e32 v41, 0x3c800000, v41
	v_cos_f32_e32 v42, v41
	v_sin_f32_e32 v43, v41
	v_add_u32_e32 v120, v120, v122
	v_mul_f32_e32 v130, 0x3e000000, v42
	v_mul_f32_e32 v194, 0x3e000000, v43
	v_and_b32_e32 v41, 63, v120
	v_cvt_f32_u32_e32 v41, v41
	v_mul_f32_e32 v41, 0x3c800000, v41
	v_cos_f32_e32 v42, v41
	v_sin_f32_e32 v43, v41
	v_add_u32_e32 v120, v120, v122
	v_mul_f32_e32 v131, 0x3e000000, v42
	v_mul_f32_e32 v195, 0x3e000000, v43
	v_and_b32_e32 v41, 63, v120
	v_cvt_f32_u32_e32 v41, v41
	v_mul_f32_e32 v41, 0x3c800000, v41
	v_cos_f32_e32 v42, v41
	v_sin_f32_e32 v43, v41
	v_add_u32_e32 v120, v120, v122
	v_mul_f32_e32 v132, 0x3e000000, v42
	v_mul_f32_e32 v196, 0x3e000000, v43
	v_and_b32_e32 v41, 63, v120
	v_cvt_f32_u32_e32 v41, v41
	v_mul_f32_e32 v41, 0x3c800000, v41
	v_cos_f32_e32 v42, v41
	v_sin_f32_e32 v43, v41
	v_add_u32_e32 v120, v120, v122
	v_mul_f32_e32 v133, 0x3e000000, v42
	v_mul_f32_e32 v197, 0x3e000000, v43
	v_and_b32_e32 v41, 63, v120
	v_cvt_f32_u32_e32 v41, v41
	v_mul_f32_e32 v41, 0x3c800000, v41
	v_cos_f32_e32 v42, v41
	v_sin_f32_e32 v43, v41
	v_add_u32_e32 v120, v120, v122
	v_mul_f32_e32 v134, 0x3e000000, v42
	v_mul_f32_e32 v198, 0x3e000000, v43
	v_and_b32_e32 v41, 63, v120
	v_cvt_f32_u32_e32 v41, v41
	v_mul_f32_e32 v41, 0x3c800000, v41
	v_cos_f32_e32 v42, v41
	v_sin_f32_e32 v43, v41
	v_add_u32_e32 v120, v120, v122
	v_mul_f32_e32 v135, 0x3e000000, v42
	v_mul_f32_e32 v199, 0x3e000000, v43
	v_and_b32_e32 v41, 63, v120
	v_cvt_f32_u32_e32 v41, v41
	v_mul_f32_e32 v41, 0x3c800000, v41
	v_cos_f32_e32 v42, v41
	v_sin_f32_e32 v43, v41
	v_add_u32_e32 v120, v120, v122
	v_mul_f32_e32 v136, 0x3e000000, v42
	v_mul_f32_e32 v204, 0x3e000000, v43
	v_and_b32_e32 v41, 63, v120
	v_cvt_f32_u32_e32 v41, v41
	v_mul_f32_e32 v41, 0x3c800000, v41
	v_cos_f32_e32 v42, v41
	v_sin_f32_e32 v43, v41
	v_add_u32_e32 v120, v120, v122
	v_mul_f32_e32 v137, 0x3e000000, v42
	v_mul_f32_e32 v205, 0x3e000000, v43
	v_and_b32_e32 v41, 63, v120
	v_cvt_f32_u32_e32 v41, v41
	v_mul_f32_e32 v41, 0x3c800000, v41
	v_cos_f32_e32 v42, v41
	v_sin_f32_e32 v43, v41
	v_add_u32_e32 v120, v120, v122
	v_mul_f32_e32 v138, 0x3e000000, v42
	v_mul_f32_e32 v206, 0x3e000000, v43
	v_and_b32_e32 v41, 63, v120
	v_cvt_f32_u32_e32 v41, v41
	v_mul_f32_e32 v41, 0x3c800000, v41
	v_cos_f32_e32 v42, v41
	v_sin_f32_e32 v43, v41
	v_add_u32_e32 v120, v120, v122
	v_mul_f32_e32 v139, 0x3e000000, v42
	v_mul_f32_e32 v207, 0x3e000000, v43
	v_and_b32_e32 v41, 63, v120
	v_cvt_f32_u32_e32 v41, v41
	v_mul_f32_e32 v41, 0x3c800000, v41
	v_cos_f32_e32 v42, v41
	v_sin_f32_e32 v43, v41
	v_add_u32_e32 v120, v120, v122
	v_mul_f32_e32 v140, 0x3e000000, v42
	v_mul_f32_e32 v208, 0x3e000000, v43
	v_and_b32_e32 v41, 63, v120
	v_cvt_f32_u32_e32 v41, v41
	v_mul_f32_e32 v41, 0x3c800000, v41
	v_cos_f32_e32 v42, v41
	v_sin_f32_e32 v43, v41
	v_add_u32_e32 v120, v120, v122
	v_mul_f32_e32 v141, 0x3e000000, v42
	v_mul_f32_e32 v209, 0x3e000000, v43
	v_and_b32_e32 v41, 63, v120
	v_cvt_f32_u32_e32 v41, v41
	v_mul_f32_e32 v41, 0x3c800000, v41
	v_cos_f32_e32 v42, v41
	v_sin_f32_e32 v43, v41
	v_add_u32_e32 v120, v120, v122
	v_mul_f32_e32 v142, 0x3e000000, v42
	v_mul_f32_e32 v210, 0x3e000000, v43
	v_and_b32_e32 v41, 63, v120
	v_cvt_f32_u32_e32 v41, v41
	v_mul_f32_e32 v41, 0x3c800000, v41
	v_cos_f32_e32 v42, v41
	v_sin_f32_e32 v43, v41
	v_add_u32_e32 v120, v120, v122
	v_mul_f32_e32 v143, 0x3e000000, v42
	v_mul_f32_e32 v211, 0x3e000000, v43
	v_and_b32_e32 v41, 63, v120
	v_cvt_f32_u32_e32 v41, v41
	v_mul_f32_e32 v41, 0x3c800000, v41
	v_cos_f32_e32 v42, v41
	v_sin_f32_e32 v43, v41
	v_add_u32_e32 v120, v120, v122
	v_mul_f32_e32 v144, 0x3e000000, v42
	v_mul_f32_e32 v212, 0x3e000000, v43
	v_and_b32_e32 v41, 63, v120
	v_cvt_f32_u32_e32 v41, v41
	v_mul_f32_e32 v41, 0x3c800000, v41
	v_cos_f32_e32 v42, v41
	v_sin_f32_e32 v43, v41
	v_add_u32_e32 v120, v120, v122
	v_mul_f32_e32 v145, 0x3e000000, v42
	v_mul_f32_e32 v213, 0x3e000000, v43
	v_and_b32_e32 v41, 63, v120
	v_cvt_f32_u32_e32 v41, v41
	v_mul_f32_e32 v41, 0x3c800000, v41
	v_cos_f32_e32 v42, v41
	v_sin_f32_e32 v43, v41
	v_add_u32_e32 v120, v120, v122
	v_mul_f32_e32 v146, 0x3e000000, v42
	v_mul_f32_e32 v214, 0x3e000000, v43
	v_and_b32_e32 v41, 63, v120
	v_cvt_f32_u32_e32 v41, v41
	v_mul_f32_e32 v41, 0x3c800000, v41
	v_cos_f32_e32 v42, v41
	v_sin_f32_e32 v43, v41
	v_add_u32_e32 v120, v120, v122
	v_mul_f32_e32 v147, 0x3e000000, v42
	v_mul_f32_e32 v215, 0x3e000000, v43
	v_and_b32_e32 v41, 63, v120
	v_cvt_f32_u32_e32 v41, v41
	v_mul_f32_e32 v41, 0x3c800000, v41
	v_cos_f32_e32 v42, v41
	v_sin_f32_e32 v43, v41
	v_add_u32_e32 v120, v120, v122
	v_mul_f32_e32 v148, 0x3e000000, v42
	v_mul_f32_e32 v216, 0x3e000000, v43
	v_and_b32_e32 v41, 63, v120
	v_cvt_f32_u32_e32 v41, v41
	v_mul_f32_e32 v41, 0x3c800000, v41
	v_cos_f32_e32 v42, v41
	v_sin_f32_e32 v43, v41
	v_add_u32_e32 v120, v120, v122
	v_mul_f32_e32 v149, 0x3e000000, v42
	v_mul_f32_e32 v217, 0x3e000000, v43
	v_and_b32_e32 v41, 63, v120
	v_cvt_f32_u32_e32 v41, v41
	v_mul_f32_e32 v41, 0x3c800000, v41
	v_cos_f32_e32 v42, v41
	v_sin_f32_e32 v43, v41
	v_add_u32_e32 v120, v120, v122
	v_mul_f32_e32 v150, 0x3e000000, v42
	v_mul_f32_e32 v218, 0x3e000000, v43
	v_and_b32_e32 v41, 63, v120
	v_cvt_f32_u32_e32 v41, v41
	v_mul_f32_e32 v41, 0x3c800000, v41
	v_cos_f32_e32 v42, v41
	v_sin_f32_e32 v43, v41
	v_add_u32_e32 v120, v120, v122
; __device__ __forceinline__ void phase_prep(const Params& P, int l, unsigned char* lds) {
;     ...
;                 const u32x4 w = *(const u32x4*)(proj + (size_t)(r0 + tok) * INW + PD_U + 8 * ch);
;                 f32x4 a0 = (f32x4){bflo(w.x), bfhi(w.x), bflo(w.y), bfhi(w.y)}, a1 = (f32x4){bflo(w.z), bfhi(w.z), bflo(w.w), bfhi(w.w)};
;     ...
; #pragma unroll 2
;             for (int c = 0; c < 64; ++c) {
;                 float cv[4], sv[4];
; #pragma unroll
;                 for (int q = 0; q < 4; ++q) { const float rev = (float)((c * (cp0 + q)) & 63) * (1.0f / 64.0f); cv[q] = __builtin_amdgcn_cosf(rev) * 0.125f; sv[q] = __builtin_amdgcn_sinf(rev) * 0.125f; }
; #pragma unroll
;                 for (int t = 0; t < 8; ++t) { const float u = ub[t * 256 + c], u2 = ub2[t * 256 + c];
; #pragma unroll
;                     for (int q = 0; q < 4; ++q) { aC[q][t] += u * cv[q]; aS[q][t] += u2 * ((t == 0 && sp0) ? cv[q] : sv[q]); } }
	v_mul_f32_e32 v151, 0x3e000000, v42
	v_mul_f32_e32 v219, 0x3e000000, v43
	v_and_b32_e32 v41, 63, v120
	v_cvt_f32_u32_e32 v41, v41
	v_mul_f32_e32 v41, 0x3c800000, v41
	v_cos_f32_e32 v42, v41
	v_sin_f32_e32 v43, v41
	v_add_u32_e32 v120, v120, v122
	v_mul_f32_e32 v152, 0x3e000000, v42
	v_mul_f32_e32 v220, 0x3e000000, v43
	v_and_b32_e32 v41, 63, v120
	v_cvt_f32_u32_e32 v41, v41
	v_mul_f32_e32 v41, 0x3c800000, v41
	v_cos_f32_e32 v42, v41
	v_sin_f32_e32 v43, v41
	v_add_u32_e32 v120, v120, v122
	v_mul_f32_e32 v153, 0x3e000000, v42
	v_mul_f32_e32 v221, 0x3e000000, v43
	v_and_b32_e32 v41, 63, v120
	v_cvt_f32_u32_e32 v41, v41
	v_mul_f32_e32 v41, 0x3c800000, v41
	v_cos_f32_e32 v42, v41
	v_sin_f32_e32 v43, v41
	v_add_u32_e32 v120, v120, v122
	v_mul_f32_e32 v154, 0x3e000000, v42
	v_mul_f32_e32 v222, 0x3e000000, v43
	v_and_b32_e32 v41, 63, v120
	v_cvt_f32_u32_e32 v41, v41
	v_mul_f32_e32 v41, 0x3c800000, v41
	v_cos_f32_e32 v42, v41
	v_sin_f32_e32 v43, v41
	v_add_u32_e32 v120, v120, v122
	v_mul_f32_e32 v155, 0x3e000000, v42
	v_mul_f32_e32 v223, 0x3e000000, v43
	v_and_b32_e32 v41, 63, v120
	v_cvt_f32_u32_e32 v41, v41
	v_mul_f32_e32 v41, 0x3c800000, v41
	v_cos_f32_e32 v42, v41
	v_sin_f32_e32 v43, v41
	v_add_u32_e32 v120, v120, v122
	v_mul_f32_e32 v156, 0x3e000000, v42
	v_mul_f32_e32 v224, 0x3e000000, v43
	v_and_b32_e32 v41, 63, v120
	v_cvt_f32_u32_e32 v41, v41
	v_mul_f32_e32 v41, 0x3c800000, v41
	v_cos_f32_e32 v42, v41
	v_sin_f32_e32 v43, v41
	v_add_u32_e32 v120, v120, v122
	v_mul_f32_e32 v157, 0x3e000000, v42
	v_mul_f32_e32 v225, 0x3e000000, v43
	v_and_b32_e32 v41, 63, v120
	v_cvt_f32_u32_e32 v41, v41
	v_mul_f32_e32 v41, 0x3c800000, v41
	v_cos_f32_e32 v42, v41
	v_sin_f32_e32 v43, v41
	v_add_u32_e32 v120, v120, v122
	v_mul_f32_e32 v158, 0x3e000000, v42
	v_mul_f32_e32 v226, 0x3e000000, v43
	v_and_b32_e32 v41, 63, v120
	v_cvt_f32_u32_e32 v41, v41
	v_mul_f32_e32 v41, 0x3c800000, v41
	v_cos_f32_e32 v42, v41
	v_sin_f32_e32 v43, v41
	v_add_u32_e32 v120, v120, v122
	v_mul_f32_e32 v159, 0x3e000000, v42
	v_mul_f32_e32 v227, 0x3e000000, v43
	v_and_b32_e32 v41, 63, v120
	v_cvt_f32_u32_e32 v41, v41
	v_mul_f32_e32 v41, 0x3c800000, v41
	v_cos_f32_e32 v42, v41
	v_sin_f32_e32 v43, v41
	v_add_u32_e32 v120, v120, v122
	v_mul_f32_e32 v160, 0x3e000000, v42
	v_mul_f32_e32 v228, 0x3e000000, v43
	v_and_b32_e32 v41, 63, v120
	v_cvt_f32_u32_e32 v41, v41
	v_mul_f32_e32 v41, 0x3c800000, v41
	v_cos_f32_e32 v42, v41
	v_sin_f32_e32 v43, v41
	v_add_u32_e32 v120, v120, v122
	v_mul_f32_e32 v161, 0x3e000000, v42
	v_mul_f32_e32 v229, 0x3e000000, v43
	s_waitcnt vmcnt(0)
	v_lshlrev_b32_e32 v45, 16, v0
	v_and_b32_e32 v46, 0xffff0000, v0
	v_lshlrev_b32_e32 v47, 16, v1
	v_and_b32_e32 v48, 0xffff0000, v1
	v_lshlrev_b32_e32 v49, 16, v2
	v_and_b32_e32 v50, 0xffff0000, v2
	v_lshlrev_b32_e32 v51, 16, v3
	v_and_b32_e32 v52, 0xffff0000, v3
	v_lshlrev_b32_e32 v53, 16, v4
	v_and_b32_e32 v54, 0xffff0000, v4
	v_lshlrev_b32_e32 v55, 16, v5
	v_and_b32_e32 v56, 0xffff0000, v5
	v_lshlrev_b32_e32 v57, 16, v6
	v_and_b32_e32 v58, 0xffff0000, v6
	v_lshlrev_b32_e32 v59, 16, v7
	v_and_b32_e32 v60, 0xffff0000, v7
	v_lshlrev_b32_e32 v61, 16, v8
	v_and_b32_e32 v62, 0xffff0000, v8
	v_lshlrev_b32_e32 v63, 16, v9
	v_and_b32_e32 v64, 0xffff0000, v9
	v_lshlrev_b32_e32 v65, 16, v10
	v_and_b32_e32 v66, 0xffff0000, v10
	v_lshlrev_b32_e32 v67, 16, v11
	v_and_b32_e32 v68, 0xffff0000, v11
	v_lshlrev_b32_e32 v69, 16, v12
	v_and_b32_e32 v70, 0xffff0000, v12
	v_lshlrev_b32_e32 v71, 16, v13
	v_and_b32_e32 v72, 0xffff0000, v13
	v_lshlrev_b32_e32 v73, 16, v14
	v_and_b32_e32 v74, 0xffff0000, v14
	v_lshlrev_b32_e32 v75, 16, v15
	v_and_b32_e32 v76, 0xffff0000, v15
	s_and_b64 vcc, exec, s[42:43]
	s_cbranch_vccz .Ldft_wr_u
; __device__ __forceinline__ void phase_prep(const Params& P, int l, unsigned char* lds) {
;     ...
;                 if (!is_ctx) {
;                     const int tg = t0 - CTX + tok, mt = (tg == 0) ? SEQ / 2 : SEQ - tg;
;                     const u32x4 m = *(const u32x4*)(proj + ((size_t)b * TT + CTX + mt) * INW + PD_U + 8 * ch);
;                     const f32x4 m0 = (f32x4){bflo(m.x), bfhi(m.x), bflo(m.y), bfhi(m.y)}, m1 = (f32x4){bflo(m.z), bfhi(m.z), bflo(m.w), bfhi(m.w)};
;                     float* d2 = U2 + tok * 256 + 8 * ch;
;                     if (tg == 0) { *(f32x4*)d2 = m0; *(f32x4*)(d2 + 4) = m1; }
;                     else { *(f32x4*)d2 = a0 - m0; *(f32x4*)(d2 + 4) = a1 - m1; a0 = a0 + m0; a1 = a1 + m1; }
;                 }
;                 *(f32x4*)d = a0; *(f32x4*)(d + 4) = a1;
	v_lshlrev_b32_e32 v77, 16, v16
	v_and_b32_e32 v78, 0xffff0000, v16
	v_lshlrev_b32_e32 v79, 16, v17
	v_and_b32_e32 v80, 0xffff0000, v17
	v_lshlrev_b32_e32 v81, 16, v18
	v_and_b32_e32 v82, 0xffff0000, v18
	v_lshlrev_b32_e32 v83, 16, v19
	v_and_b32_e32 v84, 0xffff0000, v19
	v_lshlrev_b32_e32 v85, 16, v20
	v_and_b32_e32 v86, 0xffff0000, v20
	v_lshlrev_b32_e32 v87, 16, v21
	v_and_b32_e32 v88, 0xffff0000, v21
	v_lshlrev_b32_e32 v89, 16, v22
	v_and_b32_e32 v90, 0xffff0000, v22
	v_lshlrev_b32_e32 v91, 16, v23
	v_and_b32_e32 v92, 0xffff0000, v23
	v_lshlrev_b32_e32 v93, 16, v24
	v_and_b32_e32 v94, 0xffff0000, v24
	v_lshlrev_b32_e32 v95, 16, v25
	v_and_b32_e32 v96, 0xffff0000, v25
	v_lshlrev_b32_e32 v97, 16, v26
	v_and_b32_e32 v98, 0xffff0000, v26
	v_lshlrev_b32_e32 v99, 16, v27
	v_and_b32_e32 v100, 0xffff0000, v27
	v_lshlrev_b32_e32 v101, 16, v28
	v_and_b32_e32 v102, 0xffff0000, v28
	v_lshlrev_b32_e32 v103, 16, v29
	v_and_b32_e32 v104, 0xffff0000, v29
	v_lshlrev_b32_e32 v105, 16, v30
	v_and_b32_e32 v106, 0xffff0000, v30
	v_lshlrev_b32_e32 v107, 16, v31
	v_and_b32_e32 v108, 0xffff0000, v31
	v_add_u32_e32 v42, s64, v32
	v_mov_b32_e32 v43, 0x100
	v_cmp_ne_u32_e64 s[50:51], v43, v42
	s_nop 1
	v_sub_f32_e32 v43, v45, v77
	v_add_f32_e32 v126, v45, v77
	v_cndmask_b32_e64 v77, v77, v43, s[50:51]
	v_cndmask_b32_e64 v45, v45, v126, s[50:51]
	v_sub_f32_e32 v43, v46, v78
	v_add_f32_e32 v126, v46, v78
	v_cndmask_b32_e64 v78, v78, v43, s[50:51]
	v_cndmask_b32_e64 v46, v46, v126, s[50:51]
	v_sub_f32_e32 v43, v47, v79
	v_add_f32_e32 v126, v47, v79
	v_cndmask_b32_e64 v79, v79, v43, s[50:51]
	v_cndmask_b32_e64 v47, v47, v126, s[50:51]
	v_sub_f32_e32 v43, v48, v80
	v_add_f32_e32 v126, v48, v80
	v_cndmask_b32_e64 v80, v80, v43, s[50:51]
	v_cndmask_b32_e64 v48, v48, v126, s[50:51]
	v_sub_f32_e32 v43, v49, v81
	v_add_f32_e32 v126, v49, v81
	v_cndmask_b32_e64 v81, v81, v43, s[50:51]
	v_cndmask_b32_e64 v49, v49, v126, s[50:51]
	v_sub_f32_e32 v43, v50, v82
	v_add_f32_e32 v126, v50, v82
	v_cndmask_b32_e64 v82, v82, v43, s[50:51]
	v_cndmask_b32_e64 v50, v50, v126, s[50:51]
	v_sub_f32_e32 v43, v51, v83
	v_add_f32_e32 v126, v51, v83
	v_cndmask_b32_e64 v83, v83, v43, s[50:51]
	v_cndmask_b32_e64 v51, v51, v126, s[50:51]
	v_sub_f32_e32 v43, v52, v84
	v_add_f32_e32 v126, v52, v84
	v_cndmask_b32_e64 v84, v84, v43, s[50:51]
	v_cndmask_b32_e64 v52, v52, v126, s[50:51]
	v_sub_f32_e32 v43, v53, v85
	v_add_f32_e32 v126, v53, v85
	v_cndmask_b32_e64 v85, v85, v43, s[50:51]
	v_cndmask_b32_e64 v53, v53, v126, s[50:51]
	v_sub_f32_e32 v43, v54, v86
	v_add_f32_e32 v126, v54, v86
	v_cndmask_b32_e64 v86, v86, v43, s[50:51]
	v_cndmask_b32_e64 v54, v54, v126, s[50:51]
	v_sub_f32_e32 v43, v55, v87
	v_add_f32_e32 v126, v55, v87
	v_cndmask_b32_e64 v87, v87, v43, s[50:51]
	v_cndmask_b32_e64 v55, v55, v126, s[50:51]
	v_sub_f32_e32 v43, v56, v88
	v_add_f32_e32 v126, v56, v88
	v_cndmask_b32_e64 v88, v88, v43, s[50:51]
	v_cndmask_b32_e64 v56, v56, v126, s[50:51]
	v_sub_f32_e32 v43, v57, v89
	v_add_f32_e32 v126, v57, v89
	v_cndmask_b32_e64 v89, v89, v43, s[50:51]
	v_cndmask_b32_e64 v57, v57, v126, s[50:51]
	v_sub_f32_e32 v43, v58, v90
	v_add_f32_e32 v126, v58, v90
	v_cndmask_b32_e64 v90, v90, v43, s[50:51]
	v_cndmask_b32_e64 v58, v58, v126, s[50:51]
	v_sub_f32_e32 v43, v59, v91
	v_add_f32_e32 v126, v59, v91
	v_cndmask_b32_e64 v91, v91, v43, s[50:51]
	v_cndmask_b32_e64 v59, v59, v126, s[50:51]
	v_sub_f32_e32 v43, v60, v92
	v_add_f32_e32 v126, v60, v92
	v_cndmask_b32_e64 v92, v92, v43, s[50:51]
	v_cndmask_b32_e64 v60, v60, v126, s[50:51]
	v_sub_f32_e32 v43, v61, v93
	v_add_f32_e32 v126, v61, v93
	v_cndmask_b32_e64 v93, v93, v43, s[50:51]
	v_cndmask_b32_e64 v61, v61, v126, s[50:51]
	v_sub_f32_e32 v43, v62, v94
	v_add_f32_e32 v126, v62, v94
	v_cndmask_b32_e64 v94, v94, v43, s[50:51]
	v_cndmask_b32_e64 v62, v62, v126, s[50:51]
	v_sub_f32_e32 v43, v63, v95
	v_add_f32_e32 v126, v63, v95
	v_cndmask_b32_e64 v95, v95, v43, s[50:51]
	v_cndmask_b32_e64 v63, v63, v126, s[50:51]
	v_sub_f32_e32 v43, v64, v96
	v_add_f32_e32 v126, v64, v96
	v_cndmask_b32_e64 v96, v96, v43, s[50:51]
	v_cndmask_b32_e64 v64, v64, v126, s[50:51]
	v_sub_f32_e32 v43, v65, v97
	v_add_f32_e32 v126, v65, v97
	v_cndmask_b32_e64 v97, v97, v43, s[50:51]
	v_cndmask_b32_e64 v65, v65, v126, s[50:51]
	v_sub_f32_e32 v43, v66, v98
	v_add_f32_e32 v126, v66, v98
	v_cndmask_b32_e64 v98, v98, v43, s[50:51]
	v_cndmask_b32_e64 v66, v66, v126, s[50:51]
	v_sub_f32_e32 v43, v67, v99
	v_add_f32_e32 v126, v67, v99
	v_cndmask_b32_e64 v99, v99, v43, s[50:51]
	v_cndmask_b32_e64 v67, v67, v126, s[50:51]
	v_sub_f32_e32 v43, v68, v100
	v_add_f32_e32 v126, v68, v100
	v_cndmask_b32_e64 v100, v100, v43, s[50:51]
	v_cndmask_b32_e64 v68, v68, v126, s[50:51]
	v_sub_f32_e32 v43, v69, v101
	v_add_f32_e32 v126, v69, v101
	v_cndmask_b32_e64 v101, v101, v43, s[50:51]
	v_cndmask_b32_e64 v69, v69, v126, s[50:51]
	v_sub_f32_e32 v43, v70, v102
	v_add_f32_e32 v126, v70, v102
	v_cndmask_b32_e64 v102, v102, v43, s[50:51]
	v_cndmask_b32_e64 v70, v70, v126, s[50:51]
	v_sub_f32_e32 v43, v71, v103
	v_add_f32_e32 v126, v71, v103
	v_cndmask_b32_e64 v103, v103, v43, s[50:51]
	v_cndmask_b32_e64 v71, v71, v126, s[50:51]
	v_sub_f32_e32 v43, v72, v104
	v_add_f32_e32 v126, v72, v104
	v_cndmask_b32_e64 v104, v104, v43, s[50:51]
	v_cndmask_b32_e64 v72, v72, v126, s[50:51]
	v_sub_f32_e32 v43, v73, v105
	v_add_f32_e32 v126, v73, v105
	v_cndmask_b32_e64 v105, v105, v43, s[50:51]
	v_cndmask_b32_e64 v73, v73, v126, s[50:51]
	v_sub_f32_e32 v43, v74, v106
	v_add_f32_e32 v126, v74, v106
	v_cndmask_b32_e64 v106, v106, v43, s[50:51]
	v_cndmask_b32_e64 v74, v74, v126, s[50:51]
	v_sub_f32_e32 v43, v75, v107
	v_add_f32_e32 v126, v75, v107
	v_cndmask_b32_e64 v107, v107, v43, s[50:51]
	v_cndmask_b32_e64 v75, v75, v126, s[50:51]
	v_sub_f32_e32 v43, v76, v108
	v_add_f32_e32 v126, v76, v108
	v_cndmask_b32_e64 v108, v108, v43, s[50:51]
	v_cndmask_b32_e64 v76, v76, v126, s[50:51]
	ds_write_b32 v36, v77
	ds_write_b32 v36, v78 offset:256
	ds_write_b32 v36, v79 offset:512
	ds_write_b32 v36, v80 offset:768
	ds_write_b32 v36, v81 offset:1024
	ds_write_b32 v36, v82 offset:1280
	ds_write_b32 v36, v83 offset:1536
	ds_write_b32 v36, v84 offset:1792
	ds_write_b32 v36, v85 offset:2048
	ds_write_b32 v36, v86 offset:2304
	ds_write_b32 v36, v87 offset:2560
	ds_write_b32 v36, v88 offset:2816
	ds_write_b32 v36, v89 offset:3072
	ds_write_b32 v36, v90 offset:3328
	ds_write_b32 v36, v91 offset:3584
	ds_write_b32 v36, v92 offset:3840
	ds_write_b32 v36, v93 offset:4096
	ds_write_b32 v36, v94 offset:4352
	ds_write_b32 v36, v95 offset:4608
	ds_write_b32 v36, v96 offset:4864
	ds_write_b32 v36, v97 offset:5120
	ds_write_b32 v36, v98 offset:5376
	ds_write_b32 v36, v99 offset:5632
	ds_write_b32 v36, v100 offset:5888
	ds_write_b32 v36, v101 offset:6144
	ds_write_b32 v36, v102 offset:6400
	ds_write_b32 v36, v103 offset:6656
	ds_write_b32 v36, v104 offset:6912
	ds_write_b32 v36, v105 offset:7168
	ds_write_b32 v36, v106 offset:7424
	ds_write_b32 v36, v107 offset:7680
	ds_write_b32 v36, v108 offset:7936

; __device__ __forceinline__ void phase_prep(const Params& P, int l, unsigned char* lds) {
;     ...
; #pragma unroll 2
;             for (int c = 0; c < 64; ++c) {
;                 float cv[4], sv[4];
; #pragma unroll
;                 for (int q = 0; q < 4; ++q) { const float rev = (float)((c * (cp0 + q)) & 63) * (1.0f / 64.0f); cv[q] = __builtin_amdgcn_cosf(rev) * 0.125f; sv[q] = __builtin_amdgcn_sinf(rev) * 0.125f; }
; #pragma unroll
;                 for (int t = 0; t < 8; ++t) { const float u = ub[t * 256 + c], u2 = ub2[t * 256 + c];
; #pragma unroll
;                     for (int q = 0; q < 4; ++q) { aC[q][t] += u * cv[q]; aS[q][t] += u2 * ((t == 0 && sp0) ? cv[q] : sv[q]); } }
;             }
.Ldft_lat_a:
	ds_read_b32 v37, v35
	ds_read_b32 v38, v36
	ds_read_b32 v39, v35 offset:512
	ds_read_b32 v40, v36 offset:512
	s_waitcnt lgkmcnt(2)
	v_mfma_f32_32x32x2_f32 v[0:15], v37, v130, 0
	v_mfma_f32_32x32x2_f32 v[46:61], v38, v194, 0
	ds_read_b32 v37, v35 offset:1024
	ds_read_b32 v38, v36 offset:1024
	s_waitcnt lgkmcnt(2)
	v_mfma_f32_32x32x2_f32 v[0:15], v39, v131, v[0:15]
	v_mfma_f32_32x32x2_f32 v[46:61], v40, v195, v[46:61]
	ds_read_b32 v39, v35 offset:1536
	ds_read_b32 v40, v36 offset:1536
	s_waitcnt lgkmcnt(2)
	v_mfma_f32_32x32x2_f32 v[0:15], v37, v132, v[0:15]
	v_mfma_f32_32x32x2_f32 v[46:61], v38, v196, v[46:61]
	ds_read_b32 v37, v35 offset:2048
	ds_read_b32 v38, v36 offset:2048
	s_waitcnt lgkmcnt(2)
	v_mfma_f32_32x32x2_f32 v[0:15], v39, v133, v[0:15]
	v_mfma_f32_32x32x2_f32 v[46:61], v40, v197, v[46:61]
	ds_read_b32 v39, v35 offset:2560
	ds_read_b32 v40, v36 offset:2560
	s_waitcnt lgkmcnt(2)
	v_mfma_f32_32x32x2_f32 v[0:15], v37, v134, v[0:15]
	v_mfma_f32_32x32x2_f32 v[46:61], v38, v198, v[46:61]
	ds_read_b32 v37, v35 offset:3072
	ds_read_b32 v38, v36 offset:3072
	s_waitcnt lgkmcnt(2)
	v_mfma_f32_32x32x2_f32 v[0:15], v39, v135, v[0:15]
	v_mfma_f32_32x32x2_f32 v[46:61], v40, v199, v[46:61]
	ds_read_b32 v39, v35 offset:3584
	ds_read_b32 v40, v36 offset:3584
	s_waitcnt lgkmcnt(2)
	v_mfma_f32_32x32x2_f32 v[0:15], v37, v136, v[0:15]
	v_mfma_f32_32x32x2_f32 v[46:61], v38, v204, v[46:61]
	ds_read_b32 v37, v35 offset:4096
	ds_read_b32 v38, v36 offset:4096
	s_waitcnt lgkmcnt(2)
	v_mfma_f32_32x32x2_f32 v[0:15], v39, v137, v[0:15]
	v_mfma_f32_32x32x2_f32 v[46:61], v40, v205, v[46:61]
	ds_read_b32 v39, v35 offset:4608
	ds_read_b32 v40, v36 offset:4608
	s_waitcnt lgkmcnt(2)
	v_mfma_f32_32x32x2_f32 v[0:15], v37, v138, v[0:15]
	v_mfma_f32_32x32x2_f32 v[46:61], v38, v206, v[46:61]
	ds_read_b32 v37, v35 offset:5120
	ds_read_b32 v38, v36 offset:5120
	s_waitcnt lgkmcnt(2)
	v_mfma_f32_32x32x2_f32 v[0:15], v39, v139, v[0:15]
	v_mfma_f32_32x32x2_f32 v[46:61], v40, v207, v[46:61]
	ds_read_b32 v39, v35 offset:5632
	ds_read_b32 v40, v36 offset:5632
	s_waitcnt lgkmcnt(2)
	v_mfma_f32_32x32x2_f32 v[0:15], v37, v140, v[0:15]
	v_mfma_f32_32x32x2_f32 v[46:61], v38, v208, v[46:61]
	ds_read_b32 v37, v35 offset:6144
	ds_read_b32 v38, v36 offset:6144
	s_waitcnt lgkmcnt(2)
	v_mfma_f32_32x32x2_f32 v[0:15], v39, v141, v[0:15]
	v_mfma_f32_32x32x2_f32 v[46:61], v40, v209, v[46:61]
	ds_read_b32 v39, v35 offset:6656
	ds_read_b32 v40, v36 offset:6656
	s_waitcnt lgkmcnt(2)
	v_mfma_f32_32x32x2_f32 v[0:15], v37, v142, v[0:15]
	v_mfma_f32_32x32x2_f32 v[46:61], v38, v210, v[46:61]
	ds_read_b32 v37, v35 offset:7168
	ds_read_b32 v38, v36 offset:7168
	s_waitcnt lgkmcnt(2)
	v_mfma_f32_32x32x2_f32 v[0:15], v39, v143, v[0:15]
	v_mfma_f32_32x32x2_f32 v[46:61], v40, v211, v[46:61]
	ds_read_b32 v39, v35 offset:7680
	ds_read_b32 v40, v36 offset:7680
	s_waitcnt lgkmcnt(2)
	v_mfma_f32_32x32x2_f32 v[0:15], v37, v144, v[0:15]
	v_mfma_f32_32x32x2_f32 v[46:61], v38, v212, v[46:61]
	ds_read_b32 v37, v35 offset:8192
	ds_read_b32 v38, v36 offset:8192
	s_waitcnt lgkmcnt(2)
	v_mfma_f32_32x32x2_f32 v[0:15], v39, v145, v[0:15]
	v_mfma_f32_32x32x2_f32 v[46:61], v40, v213, v[46:61]
	ds_read_b32 v39, v35 offset:8704
	ds_read_b32 v40, v36 offset:8704
	s_waitcnt lgkmcnt(2)
	v_mfma_f32_32x32x2_f32 v[0:15], v37, v146, v[0:15]
	v_mfma_f32_32x32x2_f32 v[46:61], v38, v214, v[46:61]
	ds_read_b32 v37, v35 offset:9216
	ds_read_b32 v38, v36 offset:9216
	s_waitcnt lgkmcnt(2)
	v_mfma_f32_32x32x2_f32 v[0:15], v39, v147, v[0:15]
	v_mfma_f32_32x32x2_f32 v[46:61], v40, v215, v[46:61]
	ds_read_b32 v39, v35 offset:9728
	ds_read_b32 v40, v36 offset:9728
	s_waitcnt lgkmcnt(2)
	v_mfma_f32_32x32x2_f32 v[0:15], v37, v148, v[0:15]
	v_mfma_f32_32x32x2_f32 v[46:61], v38, v216, v[46:61]
	ds_read_b32 v37, v35 offset:10240
	ds_read_b32 v38, v36 offset:10240
	s_waitcnt lgkmcnt(2)
	v_mfma_f32_32x32x2_f32 v[0:15], v39, v149, v[0:15]
	v_mfma_f32_32x32x2_f32 v[46:61], v40, v217, v[46:61]
	ds_read_b32 v39, v35 offset:10752
	ds_read_b32 v40, v36 offset:10752
	s_waitcnt lgkmcnt(2)
	v_mfma_f32_32x32x2_f32 v[0:15], v37, v150, v[0:15]
	v_mfma_f32_32x32x2_f32 v[46:61], v38, v218, v[46:61]
	ds_read_b32 v37, v35 offset:11264
	ds_read_b32 v38, v36 offset:11264
	s_waitcnt lgkmcnt(2)
	v_mfma_f32_32x32x2_f32 v[0:15], v39, v151, v[0:15]
	v_mfma_f32_32x32x2_f32 v[46:61], v40, v219, v[46:61]
	ds_read_b32 v39, v35 offset:11776
	ds_read_b32 v40, v36 offset:11776
	s_waitcnt lgkmcnt(2)
	v_mfma_f32_32x32x2_f32 v[0:15], v37, v152, v[0:15]
	v_mfma_f32_32x32x2_f32 v[46:61], v38, v220, v[46:61]
	ds_read_b32 v37, v35 offset:12288
	ds_read_b32 v38, v36 offset:12288
	s_waitcnt lgkmcnt(2)
	v_mfma_f32_32x32x2_f32 v[0:15], v39, v153, v[0:15]
	v_mfma_f32_32x32x2_f32 v[46:61], v40, v221, v[46:61]
	ds_read_b32 v39, v35 offset:12800
	ds_read_b32 v40, v36 offset:12800
	s_waitcnt lgkmcnt(2)
	v_mfma_f32_32x32x2_f32 v[0:15], v37, v154, v[0:15]
	v_mfma_f32_32x32x2_f32 v[46:61], v38, v222, v[46:61]
	ds_read_b32 v37, v35 offset:13312
	ds_read_b32 v38, v36 offset:13312
	s_waitcnt lgkmcnt(2)
	v_mfma_f32_32x32x2_f32 v[0:15], v39, v155, v[0:15]
	v_mfma_f32_32x32x2_f32 v[46:61], v40, v223, v[46:61]
	ds_read_b32 v39, v35 offset:13824
	ds_read_b32 v40, v36 offset:13824
	s_waitcnt lgkmcnt(2)
	v_mfma_f32_32x32x2_f32 v[0:15], v37, v156, v[0:15]
	v_mfma_f32_32x32x2_f32 v[46:61], v38, v224, v[46:61]
	ds_read_b32 v37, v35 offset:14336
	ds_read_b32 v38, v36 offset:14336
	s_waitcnt lgkmcnt(2)
	v_mfma_f32_32x32x2_f32 v[0:15], v39, v157, v[0:15]
	v_mfma_f32_32x32x2_f32 v[46:61], v40, v225, v[46:61]
	ds_read_b32 v39, v35 offset:14848
	ds_read_b32 v40, v36 offset:14848
	s_waitcnt lgkmcnt(2)
; __device__ __forceinline__ void phase_prep(const Params& P, int l, unsigned char* lds) {
;     ...
;             for (int c = 0; c < 64; ++c) {
;                 float cv[4], sv[4];
; #pragma unroll
;                 for (int q = 0; q < 4; ++q) { const float rev = (float)((c * (cp0 + q)) & 63) * (1.0f / 64.0f); cv[q] = __builtin_amdgcn_cosf(rev) * 0.125f; sv[q] = __builtin_amdgcn_sinf(rev) * 0.125f; }
; #pragma unroll
;                 for (int t = 0; t < 8; ++t) { const float u = ub[t * 256 + c], u2 = ub2[t * 256 + c];
; #pragma unroll
;                     for (int q = 0; q < 4; ++q) { aC[q][t] += u * cv[q]; aS[q][t] += u2 * ((t == 0 && sp0) ? cv[q] : sv[q]); } }
;             }
	v_mfma_f32_32x32x2_f32 v[0:15], v37, v158, v[0:15]
	v_mfma_f32_32x32x2_f32 v[46:61], v38, v226, v[46:61]
	ds_read_b32 v37, v35 offset:15360
	ds_read_b32 v38, v36 offset:15360
	s_waitcnt lgkmcnt(2)
	v_mfma_f32_32x32x2_f32 v[0:15], v39, v159, v[0:15]
	v_mfma_f32_32x32x2_f32 v[46:61], v40, v227, v[46:61]
	ds_read_b32 v39, v35 offset:15872
	ds_read_b32 v40, v36 offset:15872
	s_waitcnt lgkmcnt(2)
	v_mfma_f32_32x32x2_f32 v[0:15], v37, v160, v[0:15]
	v_mfma_f32_32x32x2_f32 v[46:61], v38, v228, v[46:61]
	s_waitcnt lgkmcnt(0)
	v_mfma_f32_32x32x2_f32 v[0:15], v39, v161, v[0:15]
	v_mfma_f32_32x32x2_f32 v[46:61], v40, v229, v[46:61]
	v_lshlrev_b32_e32 v98, 13, v33
	v_lshl_add_u32 v98, v34, 2, v98
	s_lshl_b32 s7, s15, 14
	s_lshl_b32 s18, s13, 7
	s_add_u32 s7, s7, s18
	s_add_u32 s7, s7, 0
	v_add_u32_e32 v98, s7, v98
	ds_read_b32 v100, v98
	ds_read_b32 v101, v98 offset:256
	ds_read_b32 v102, v98 offset:512
	ds_read_b32 v103, v98 offset:768
	ds_read_b32 v104, v98 offset:1024
	ds_read_b32 v105, v98 offset:1280
	ds_read_b32 v106, v98 offset:1536
	ds_read_b32 v107, v98 offset:1792
	s_waitcnt lgkmcnt(0)
	v_mov_b32_e32 v96, v100
	v_sub_f32_e32 v96, v96, v101
	v_add_f32_e32 v96, v96, v102
	v_sub_f32_e32 v96, v96, v103
	v_add_f32_e32 v96, v96, v104
	v_sub_f32_e32 v96, v96, v105
	v_add_f32_e32 v96, v96, v106
	v_sub_f32_e32 v96, v96, v107
	ds_read_b32 v100, v98 offset:2048
	ds_read_b32 v101, v98 offset:2304
	ds_read_b32 v102, v98 offset:2560
	ds_read_b32 v103, v98 offset:2816
	ds_read_b32 v104, v98 offset:3072
	ds_read_b32 v105, v98 offset:3328
	ds_read_b32 v106, v98 offset:3584
	ds_read_b32 v107, v98 offset:3840
	s_waitcnt lgkmcnt(0)
	v_add_f32_e32 v96, v96, v100
	v_sub_f32_e32 v96, v96, v101
	v_add_f32_e32 v96, v96, v102
	v_sub_f32_e32 v96, v96, v103
	v_add_f32_e32 v96, v96, v104
	v_sub_f32_e32 v96, v96, v105
	v_add_f32_e32 v96, v96, v106
	v_sub_f32_e32 v96, v96, v107
	ds_read_b32 v100, v98 offset:4096
	ds_read_b32 v101, v98 offset:4352
	ds_read_b32 v102, v98 offset:4608
	ds_read_b32 v103, v98 offset:4864
	ds_read_b32 v104, v98 offset:5120
	ds_read_b32 v105, v98 offset:5376
	ds_read_b32 v106, v98 offset:5632
	ds_read_b32 v107, v98 offset:5888
	s_waitcnt lgkmcnt(0)
	v_add_f32_e32 v96, v96, v100
	v_sub_f32_e32 v96, v96, v101
	v_add_f32_e32 v96, v96, v102
	v_sub_f32_e32 v96, v96, v103
	v_add_f32_e32 v96, v96, v104
	v_sub_f32_e32 v96, v96, v105
	v_add_f32_e32 v96, v96, v106
	v_sub_f32_e32 v96, v96, v107
	ds_read_b32 v100, v98 offset:6144
	ds_read_b32 v101, v98 offset:6400
	ds_read_b32 v102, v98 offset:6656
	ds_read_b32 v103, v98 offset:6912
	ds_read_b32 v104, v98 offset:7168
	ds_read_b32 v105, v98 offset:7424
	ds_read_b32 v106, v98 offset:7680
	ds_read_b32 v107, v98 offset:7936
	s_waitcnt lgkmcnt(0)
	v_add_f32_e32 v96, v96, v100
	v_sub_f32_e32 v96, v96, v101
	v_add_f32_e32 v96, v96, v102
	v_sub_f32_e32 v96, v96, v103
	v_add_f32_e32 v96, v96, v104
	v_sub_f32_e32 v96, v96, v105
	v_add_f32_e32 v96, v96, v106
	v_sub_f32_e32 v96, v96, v107
	v_xor_b32_e32 v99, 32, v32
	v_lshlrev_b32_e32 v99, 2, v99
	ds_bpermute_b32 v100, v99, v96
	s_waitcnt lgkmcnt(0)
	v_add_f32_e32 v96, v96, v100
	v_mul_f32_e32 v96, 0x3e000000, v96
	v_cvt_pk_bf16_f32 v96, v96, v96
	s_mov_b32 s19, 0
	s_cmp_eq_u32 s64, 0x100
	s_cbranch_scc0 .Ldft_nosp
	s_cmp_eq_u32 s13, 0
	s_cbranch_scc0 .Ldft_nosp
	s_mov_b32 s19, 1
	ds_read_b32 v38, v36
	ds_read_b32 v40, v36 offset:512
	s_waitcnt lgkmcnt(1)
	v_mfma_f32_32x32x2_f32 v[78:93], v38, v130, 0
	ds_read_b32 v38, v36 offset:1024
	s_waitcnt lgkmcnt(1)
	v_mfma_f32_32x32x2_f32 v[78:93], v40, v131, v[78:93]
	ds_read_b32 v40, v36 offset:1536
	s_waitcnt lgkmcnt(1)
	v_mfma_f32_32x32x2_f32 v[78:93], v38, v132, v[78:93]
	ds_read_b32 v38, v36 offset:2048
	s_waitcnt lgkmcnt(1)
	v_mfma_f32_32x32x2_f32 v[78:93], v40, v133, v[78:93]
	ds_read_b32 v40, v36 offset:2560
	s_waitcnt lgkmcnt(1)
	v_mfma_f32_32x32x2_f32 v[78:93], v38, v134, v[78:93]
	ds_read_b32 v38, v36 offset:3072
	s_waitcnt lgkmcnt(1)
	v_mfma_f32_32x32x2_f32 v[78:93], v40, v135, v[78:93]
	ds_read_b32 v40, v36 offset:3584
	s_waitcnt lgkmcnt(1)
	v_mfma_f32_32x32x2_f32 v[78:93], v38, v136, v[78:93]
	ds_read_b32 v38, v36 offset:4096
	s_waitcnt lgkmcnt(1)
	v_mfma_f32_32x32x2_f32 v[78:93], v40, v137, v[78:93]
	ds_read_b32 v40, v36 offset:4608
	s_waitcnt lgkmcnt(1)
	v_mfma_f32_32x32x2_f32 v[78:93], v38, v138, v[78:93]
	ds_read_b32 v38, v36 offset:5120
	s_waitcnt lgkmcnt(1)
	v_mfma_f32_32x32x2_f32 v[78:93], v40, v139, v[78:93]
	ds_read_b32 v40, v36 offset:5632
	s_waitcnt lgkmcnt(1)
	v_mfma_f32_32x32x2_f32 v[78:93], v38, v140, v[78:93]
	ds_read_b32 v38, v36 offset:6144
	s_waitcnt lgkmcnt(1)
	v_mfma_f32_32x32x2_f32 v[78:93], v40, v141, v[78:93]
	ds_read_b32 v40, v36 offset:6656
	s_waitcnt lgkmcnt(1)
	v_mfma_f32_32x32x2_f32 v[78:93], v38, v142, v[78:93]
	ds_read_b32 v38, v36 offset:7168
	s_waitcnt lgkmcnt(1)
	v_mfma_f32_32x32x2_f32 v[78:93], v40, v143, v[78:93]
	ds_read_b32 v40, v36 offset:7680
	s_waitcnt lgkmcnt(1)
	v_mfma_f32_32x32x2_f32 v[78:93], v38, v144, v[78:93]
	ds_read_b32 v38, v36 offset:8192
	s_waitcnt lgkmcnt(1)
	v_mfma_f32_32x32x2_f32 v[78:93], v40, v145, v[78:93]
	ds_read_b32 v40, v36 offset:8704
	s_waitcnt lgkmcnt(1)
	v_mfma_f32_32x32x2_f32 v[78:93], v38, v146, v[78:93]
	ds_read_b32 v38, v36 offset:9216
	s_waitcnt lgkmcnt(1)
	v_mfma_f32_32x32x2_f32 v[78:93], v40, v147, v[78:93]
	ds_read_b32 v40, v36 offset:9728
	s_waitcnt lgkmcnt(1)
	v_mfma_f32_32x32x2_f32 v[78:93], v38, v148, v[78:93]
	ds_read_b32 v38, v36 offset:10240
	s_waitcnt lgkmcnt(1)
	v_mfma_f32_32x32x2_f32 v[78:93], v40, v149, v[78:93]
	ds_read_b32 v40, v36 offset:10752
	s_waitcnt lgkmcnt(1)
	v_mfma_f32_32x32x2_f32 v[78:93], v38, v150, v[78:93]
	ds_read_b32 v38, v36 offset:11264
	s_waitcnt lgkmcnt(1)
; __device__ __forceinline__ unsigned pk2(float lo, float hi) { f32x2_t v = {lo, hi}; bf16x2_t b = __builtin_convertvector(v, bf16x2_t); return __builtin_bit_cast(unsigned, b); }
; __device__ __forceinline__ void phase_prep(const Params& P, int l, unsigned char* lds) {
;     ...
;                     for (int q = 0; q < 4; ++q) { aC[q][t] += u * cv[q]; aS[q][t] += u2 * ((t == 0 && sp0) ? cv[q] : sv[q]); } }
;             }
; #pragma unroll
;             for (int q = 0; q < 4; ++q) {
;                 const int n = n0 + q;
;                 bf16_t* dC; bf16_t* dS;
;                 if (is_ctx) { bf16_t* z = (bf16_t*)(P.ws + WS_ZCT) + ((size_t)b * 256 + n) * 512 + t0 + t8; dC = z; dS = z + 256; }
;                 else { bf16_t* z = (bf16_t*)(P.ws + WS_ZT) + ((size_t)b * 256 + n) * 2048 + (t0 - CTX) + t8; dC = z; dS = z + 1024; }
;                 u32x4 o; o.x = pk2(aC[q][0], aC[q][1]); o.y = pk2(aC[q][2], aC[q][3]); o.z = pk2(aC[q][4], aC[q][5]); o.w = pk2(aC[q][6], aC[q][7]);
;                 *(u32x4*)dC = o;
;                 u32x4 s4; s4.x = pk2(aS[q][0], aS[q][1]); s4.y = pk2(aS[q][2], aS[q][3]); s4.z = pk2(aS[q][4], aS[q][5]); s4.w = pk2(aS[q][6], aS[q][7]);
;                 *(u32x4*)dS = s4;
	v_mfma_f32_32x32x2_f32 v[78:93], v40, v151, v[78:93]
	ds_read_b32 v40, v36 offset:11776
	s_waitcnt lgkmcnt(1)
	v_mfma_f32_32x32x2_f32 v[78:93], v38, v152, v[78:93]
	ds_read_b32 v38, v36 offset:12288
	s_waitcnt lgkmcnt(1)
	v_mfma_f32_32x32x2_f32 v[78:93], v40, v153, v[78:93]
	ds_read_b32 v40, v36 offset:12800
	s_waitcnt lgkmcnt(1)
	v_mfma_f32_32x32x2_f32 v[78:93], v38, v154, v[78:93]
	ds_read_b32 v38, v36 offset:13312
	s_waitcnt lgkmcnt(1)
	v_mfma_f32_32x32x2_f32 v[78:93], v40, v155, v[78:93]
	ds_read_b32 v40, v36 offset:13824
	s_waitcnt lgkmcnt(1)
	v_mfma_f32_32x32x2_f32 v[78:93], v38, v156, v[78:93]
	ds_read_b32 v38, v36 offset:14336
	s_waitcnt lgkmcnt(1)
	v_mfma_f32_32x32x2_f32 v[78:93], v40, v157, v[78:93]
	ds_read_b32 v40, v36 offset:14848
	s_waitcnt lgkmcnt(1)
	v_mfma_f32_32x32x2_f32 v[78:93], v38, v158, v[78:93]
	ds_read_b32 v38, v36 offset:15360
	s_waitcnt lgkmcnt(1)
	v_mfma_f32_32x32x2_f32 v[78:93], v40, v159, v[78:93]
	ds_read_b32 v40, v36 offset:15872
	s_waitcnt lgkmcnt(1)
	v_mfma_f32_32x32x2_f32 v[78:93], v38, v160, v[78:93]
	s_waitcnt lgkmcnt(0)
	v_mfma_f32_32x32x2_f32 v[78:93], v40, v161, v[78:93]
	v_lshlrev_b32_e32 v98, 13, v33
	v_lshl_add_u32 v98, v34, 2, v98
	s_lshl_b32 s7, s15, 14
	s_lshl_b32 s18, s13, 7
	s_add_u32 s7, s7, s18
	s_add_u32 s7, s7, 65536
	v_add_u32_e32 v98, s7, v98
	ds_read_b32 v100, v98
	ds_read_b32 v101, v98 offset:256
	ds_read_b32 v102, v98 offset:512
	ds_read_b32 v103, v98 offset:768
	ds_read_b32 v104, v98 offset:1024
	ds_read_b32 v105, v98 offset:1280
	ds_read_b32 v106, v98 offset:1536
	ds_read_b32 v107, v98 offset:1792
	s_waitcnt lgkmcnt(0)
	v_mov_b32_e32 v97, v100
	v_sub_f32_e32 v97, v97, v101
	v_add_f32_e32 v97, v97, v102
	v_sub_f32_e32 v97, v97, v103
	v_add_f32_e32 v97, v97, v104
	v_sub_f32_e32 v97, v97, v105
	v_add_f32_e32 v97, v97, v106
	v_sub_f32_e32 v97, v97, v107
	ds_read_b32 v100, v98 offset:2048
	ds_read_b32 v101, v98 offset:2304
	ds_read_b32 v102, v98 offset:2560
	ds_read_b32 v103, v98 offset:2816
	ds_read_b32 v104, v98 offset:3072
	ds_read_b32 v105, v98 offset:3328
	ds_read_b32 v106, v98 offset:3584
	ds_read_b32 v107, v98 offset:3840
	s_waitcnt lgkmcnt(0)
	v_add_f32_e32 v97, v97, v100
	v_sub_f32_e32 v97, v97, v101
	v_add_f32_e32 v97, v97, v102
	v_sub_f32_e32 v97, v97, v103
	v_add_f32_e32 v97, v97, v104
	v_sub_f32_e32 v97, v97, v105
	v_add_f32_e32 v97, v97, v106
	v_sub_f32_e32 v97, v97, v107
	ds_read_b32 v100, v98 offset:4096
	ds_read_b32 v101, v98 offset:4352
	ds_read_b32 v102, v98 offset:4608
	ds_read_b32 v103, v98 offset:4864
	ds_read_b32 v104, v98 offset:5120
	ds_read_b32 v105, v98 offset:5376
	ds_read_b32 v106, v98 offset:5632
	ds_read_b32 v107, v98 offset:5888
	s_waitcnt lgkmcnt(0)
	v_add_f32_e32 v97, v97, v100
	v_sub_f32_e32 v97, v97, v101
	v_add_f32_e32 v97, v97, v102
	v_sub_f32_e32 v97, v97, v103
	v_add_f32_e32 v97, v97, v104
	v_sub_f32_e32 v97, v97, v105
	v_add_f32_e32 v97, v97, v106
	v_sub_f32_e32 v97, v97, v107
	ds_read_b32 v100, v98 offset:6144
	ds_read_b32 v101, v98 offset:6400
	ds_read_b32 v102, v98 offset:6656
	ds_read_b32 v103, v98 offset:6912
	ds_read_b32 v104, v98 offset:7168
	ds_read_b32 v105, v98 offset:7424
	ds_read_b32 v106, v98 offset:7680
	ds_read_b32 v107, v98 offset:7936
	s_waitcnt lgkmcnt(0)
	v_add_f32_e32 v97, v97, v100
	v_sub_f32_e32 v97, v97, v101
	v_add_f32_e32 v97, v97, v102
	v_sub_f32_e32 v97, v97, v103
	v_add_f32_e32 v97, v97, v104
	v_sub_f32_e32 v97, v97, v105
	v_add_f32_e32 v97, v97, v106
	v_sub_f32_e32 v97, v97, v107
	v_xor_b32_e32 v99, 32, v32
	v_lshlrev_b32_e32 v99, 2, v99
	ds_bpermute_b32 v100, v99, v97
	s_waitcnt lgkmcnt(0)
	v_add_f32_e32 v97, v97, v100
	v_mul_f32_e32 v97, 0x3e000000, v97
	v_cvt_pk_bf16_f32 v97, v97, v97
.Ldft_nosp:
	s_nop 15
	s_nop 7
	v_cvt_pk_bf16_f32 v16, v0, v1
	v_cvt_pk_bf16_f32 v17, v2, v3
	v_cvt_pk_bf16_f32 v18, v4, v5
	v_cvt_pk_bf16_f32 v19, v6, v7
	v_cvt_pk_bf16_f32 v20, v8, v9
	v_cvt_pk_bf16_f32 v21, v10, v11
	v_cvt_pk_bf16_f32 v22, v12, v13
	v_cvt_pk_bf16_f32 v23, v14, v15
	v_cvt_pk_bf16_f32 v24, v46, v47
	v_cvt_pk_bf16_f32 v25, v48, v49
	v_cvt_pk_bf16_f32 v26, v50, v51
	v_cvt_pk_bf16_f32 v27, v52, v53
	v_cvt_pk_bf16_f32 v28, v54, v55
	v_cvt_pk_bf16_f32 v29, v56, v57
	v_cvt_pk_bf16_f32 v30, v58, v59
	v_cvt_pk_bf16_f32 v31, v60, v61
	v_cvt_pk_bf16_f32 v78, v78, v78
	s_and_b64 vcc, exec, s[42:43]
	s_cbranch_vccz .Ldft_out_ctx
	s_lshl_b32 s7, s36, 8
	s_lshl_b32 s18, s15, 6
	s_add_u32 s7, s7, s18
	s_mul_i32 s7, s7, 4096
	s_sub_u32 s18, s64, 256
	s_lshl_b32 s12, s13, 5
	s_add_u32 s18, s18, s12
	s_lshl_b32 s18, s18, 1
	s_add_u32 s7, s7, s18
	s_add_u32 s40, s0, s7
	s_addc_u32 s41, s1, 0
	s_add_u32 s40, s40, 0x17e00000
	s_addc_u32 s41, s41, 0
	v_lshlrev_b32_e32 v124, 12, v34
	v_lshl_add_u32 v124, v33, 3, v124
	v_sub_u32_e32 v125, 64, v34
	v_lshlrev_b32_e32 v125, 12, v125
	v_lshl_add_u32 v125, v33, 3, v125
	v_lshlrev_b32_e32 v41, 1, v34
	v_add_u32_e32 v41, 0x20000, v41
	global_store_dwordx2 v124, v[16:17], s[40:41]
	global_store_dwordx2 v124, v[18:19], s[40:41] offset:16
	global_store_dwordx2 v124, v[20:21], s[40:41] offset:32
	global_store_dwordx2 v124, v[22:23], s[40:41] offset:48
	global_store_dwordx2 v124, v[24:25], s[40:41] offset:2048
	global_store_dwordx2 v124, v[26:27], s[40:41] offset:2064
	global_store_dwordx2 v124, v[28:29], s[40:41] offset:2080
	global_store_dwordx2 v124, v[30:31], s[40:41] offset:2096
	v_cmp_gt_u32_e32 vcc, 32, v32
	s_and_saveexec_b64 s[50:51], vcc
	global_store_short v41, v96, s[40:41]
	global_store_short v41, v129, s[40:41] offset:2048
	s_or_b64 exec, exec, s[50:51]
	v_xor_b32_e32 v24, 0x80008000, v24
	v_xor_b32_e32 v25, 0x80008000, v25
	v_xor_b32_e32 v26, 0x80008000, v26
	v_xor_b32_e32 v27, 0x80008000, v27
	v_xor_b32_e32 v28, 0x80008000, v28
	v_xor_b32_e32 v29, 0x80008000, v29
	v_xor_b32_e32 v30, 0x80008000, v30
	v_xor_b32_e32 v31, 0x80008000, v31
	v_cmp_ne_u32_e32 vcc, 0, v34
	s_and_saveexec_b64 s[50:51], vcc
	global_store_dwordx2 v125, v[16:17], s[40:41]
	global_store_dwordx2 v125, v[18:19], s[40:41] offset:16
	global_store_dwordx2 v125, v[20:21], s[40:41] offset:32
	global_store_dwordx2 v125, v[22:23], s[40:41] offset:48
	global_store_dwordx2 v125, v[24:25], s[40:41] offset:2048
	global_store_dwordx2 v125, v[26:27], s[40:41] offset:2064
	global_store_dwordx2 v125, v[28:29], s[40:41] offset:2080
	global_store_dwordx2 v125, v[30:31], s[40:41] offset:2096
	s_or_b64 exec, exec, s[50:51]
	s_cmp_eq_u32 s19, 0
	s_cbranch_scc1 .Ldft_fix_lat
	v_lshlrev_b32_e32 v42, 12, v34
	v_sub_u32_e32 v43, 64, v34
	v_lshlrev_b32_e32 v43, 12, v43
	v_cmp_gt_u32_e32 vcc, 32, v32
	s_and_saveexec_b64 s[50:51], vcc
	global_store_short v42, v78, s[40:41] offset:2048
	v_cmp_ne_u32_e32 vcc, 0, v34
	s_and_b64 exec, exec, vcc
	global_store_short v43, v78, s[40:41] offset:2048
	s_or_b64 exec, exec, s[50:51]
	v_cmp_eq_u32_e32 vcc, 0, v32
	s_and_saveexec_b64 s[50:51], vcc
	v_mov_b32_e32 v42, 0x20000
	global_store_short v42, v97, s[40:41] offset:2048
	s_or_b64 exec, exec, s[50:51]

; __device__ __forceinline__ unsigned pk2(float lo, float hi) { f32x2_t v = {lo, hi}; bf16x2_t b = __builtin_convertvector(v, bf16x2_t); return __builtin_bit_cast(unsigned, b); }
; __device__ __forceinline__ void phase_prep(const Params& P, int l, unsigned char* lds) {
;     ...
; #pragma unroll
;             for (int q = 0; q < 4; ++q) {
;                 const int n = n0 + q;
;                 bf16_t* dC; bf16_t* dS;
;                 if (is_ctx) { bf16_t* z = (bf16_t*)(P.ws + WS_ZCT) + ((size_t)b * 256 + n) * 512 + t0 + t8; dC = z; dS = z + 256; }
;                 else { bf16_t* z = (bf16_t*)(P.ws + WS_ZT) + ((size_t)b * 256 + n) * 2048 + (t0 - CTX) + t8; dC = z; dS = z + 1024; }
;                 u32x4 o; o.x = pk2(aC[q][0], aC[q][1]); o.y = pk2(aC[q][2], aC[q][3]); o.z = pk2(aC[q][4], aC[q][5]); o.w = pk2(aC[q][6], aC[q][7]);
;                 *(u32x4*)dC = o;
;                 u32x4 s4; s4.x = pk2(aS[q][0], aS[q][1]); s4.y = pk2(aS[q][2], aS[q][3]); s4.z = pk2(aS[q][4], aS[q][5]); s4.w = pk2(aS[q][6], aS[q][7]);
;                 *(u32x4*)dS = s4;
;             }
.Ldft_out_ctx:
	s_lshl_b32 s7, s36, 8
	s_lshl_b32 s18, s15, 6
	s_add_u32 s7, s7, s18
	s_mul_i32 s7, s7, 1024
	s_sub_u32 s18, s64, 0
	s_lshl_b32 s12, s13, 5
	s_add_u32 s18, s18, s12
	s_lshl_b32 s18, s18, 1
	s_add_u32 s7, s7, s18
	s_add_u32 s40, s0, s7
	s_addc_u32 s41, s1, 0
	s_add_u32 s40, s40, 0x19e00000
	s_addc_u32 s41, s41, 0
	v_lshlrev_b32_e32 v124, 10, v34
	v_lshl_add_u32 v124, v33, 3, v124
	v_sub_u32_e32 v125, 64, v34
	v_lshlrev_b32_e32 v125, 10, v125
	v_lshl_add_u32 v125, v33, 3, v125
	v_lshlrev_b32_e32 v41, 1, v34
	v_add_u32_e32 v41, 0x8000, v41
	global_store_dwordx2 v124, v[16:17], s[40:41]
	global_store_dwordx2 v124, v[18:19], s[40:41] offset:16
	global_store_dwordx2 v124, v[20:21], s[40:41] offset:32
	global_store_dwordx2 v124, v[22:23], s[40:41] offset:48
	global_store_dwordx2 v124, v[24:25], s[40:41] offset:512
	global_store_dwordx2 v124, v[26:27], s[40:41] offset:528
	global_store_dwordx2 v124, v[28:29], s[40:41] offset:544
	global_store_dwordx2 v124, v[30:31], s[40:41] offset:560
	v_cmp_gt_u32_e32 vcc, 32, v32
	s_and_saveexec_b64 s[50:51], vcc
	global_store_short v41, v96, s[40:41]
	global_store_short v41, v129, s[40:41] offset:512
	s_or_b64 exec, exec, s[50:51]
	v_xor_b32_e32 v24, 0x80008000, v24
	v_xor_b32_e32 v25, 0x80008000, v25
	v_xor_b32_e32 v26, 0x80008000, v26
	v_xor_b32_e32 v27, 0x80008000, v27
	v_xor_b32_e32 v28, 0x80008000, v28
	v_xor_b32_e32 v29, 0x80008000, v29
	v_xor_b32_e32 v30, 0x80008000, v30
	v_xor_b32_e32 v31, 0x80008000, v31
	v_cmp_ne_u32_e32 vcc, 0, v34
	s_and_saveexec_b64 s[50:51], vcc
	global_store_dwordx2 v125, v[16:17], s[40:41]
	global_store_dwordx2 v125, v[18:19], s[40:41] offset:16
	global_store_dwordx2 v125, v[20:21], s[40:41] offset:32
	global_store_dwordx2 v125, v[22:23], s[40:41] offset:48
	global_store_dwordx2 v125, v[24:25], s[40:41] offset:512
	global_store_dwordx2 v125, v[26:27], s[40:41] offset:528
	global_store_dwordx2 v125, v[28:29], s[40:41] offset:544
	global_store_dwordx2 v125, v[30:31], s[40:41] offset:560
	s_or_b64 exec, exec, s[50:51]
	s_cmp_eq_u32 s19, 0
	s_cbranch_scc1 .Ldft_fix_ctx
	v_lshlrev_b32_e32 v42, 10, v34
	v_sub_u32_e32 v43, 64, v34
	v_lshlrev_b32_e32 v43, 10, v43
	v_cmp_gt_u32_e32 vcc, 32, v32
	s_and_saveexec_b64 s[50:51], vcc
	global_store_short v42, v78, s[40:41] offset:512
	v_cmp_ne_u32_e32 vcc, 0, v34
	s_and_b64 exec, exec, vcc
	global_store_short v43, v78, s[40:41] offset:512
	s_or_b64 exec, exec, s[50:51]
	v_cmp_eq_u32_e32 vcc, 0, v32
	s_and_saveexec_b64 s[50:51], vcc
	v_mov_b32_e32 v42, 0x8000
	global_store_short v42, v97, s[40:41] offset:512
	s_or_b64 exec, exec, s[50:51]
.Ldft_fix_ctx:
.Ldft_out_done:
	s_barrier
	s_mov_b64 s[38:39], 0
